# leader pre-advances its clock by 10 units across its sweep boundary
# baseline (speedup 1.0000x reference)
.Lxp_noswe:
	s_mov_b32 s80, s81
	s_mov_b32 s81, s94
	s_add_i32 s25, s25, 1
	s_cmp_eq_u32 s82, 1
	s_cbranch_scc0 .Lxp_nojump
	s_add_i32 s2, s97, 17536
	s_and_b32 s2, s2, 0x3fff
	v_mov_b32_e32 v245, s2
	s_mov_b64 exec, 1
	global_store_dword v[246:247], v245, off
	s_mov_b64 exec, -1
.Lxp_nojump:
	s_waitcnt vmcnt(0) lgkmcnt(0)
	s_lshl_b32 s2, s33, 12
	v_add_u32_e32 v249, s2, v248
	ds_write_b128 v249, v[90:93]
	ds_write_b128 v249, v[94:97] offset:1024
	ds_write_b128 v249, v[98:101] offset:2048
	ds_write_b128 v249, v[102:105] offset:3072
	v_cmp_eq_u32_e32 vcc, s33, v60
	s_nop 1
	v_cndmask_b32_e32 v243, v243, v142, vcc
	v_readlane_b32 s76, v254, 34
	v_readlane_b32 s77, v254, 35
	s_mov_b32 s25, 0
